# generic pipelined f32->bf16 weight-conversion routine used for phase 0 and for the w_down conversion by idle workgroups in the w_in GEMM phase
# baseline (speedup 1.0000x reference)
; __device__ __forceinline__ int bid_fresh() { int t = blockIdx.x; asm volatile("" : "+s"(t)); return t; }
; __device__ __forceinline__ void phase0(PP p, unsigned char* shm) {
;     unsigned char* ws = p->ws;
;     float* tile = (float*)shm;
;     constexpr int C_IN = 32 * 14, C_OUT = 32 * 8, C_XQ = 32 * 2, C_XO = 8 * 8, C_UP = 32 * 32, C_DN = 128 * 8, C_GLU = 8 * 2, C_POOL = 16, C_PW = 8 * 2;
;     constexpr int C_LAYER = C_IN + C_OUT + 3 * C_XQ + C_XO + C_UP + C_DN + C_GLU + C_POOL + C_PW;
;     for (int it = bid_fresh(); it < DEPTH * C_LAYER; it += gridDim.x) {
;         const int l = it / C_LAYER; int r = it % C_LAYER;
;         if (r < C_IN) { tconv_tile_w(p->in[5] + (size_t)l * D * INW, INW, r / 14, r % 14, (bf16_t*)(ws + WS_WIN) + (size_t)l * INW * D, D, tile, p->in[4] + (size_t)l * D); continue; } r -= C_IN;
;         if (r < C_OUT) { tconv_tile_w(p->in[23] + (size_t)l * D * D, D, r / 8, r % 8, (bf16_t*)(ws + WS_WOUT) + (size_t)l * D * D, D, tile, p->in[22] + (size_t)l * D); continue; } r -= C_OUT;
;         if (r < C_XQ) { tconv_tile_w(p->in[25] + (size_t)l * D * 512, 512, r / 2, r % 2, (bf16_t*)(ws + WS_WXQ) + (size_t)l * 512 * D, D, tile, p->in[24] + (size_t)l * D); continue; } r -= C_XQ;
;         if (r < C_XQ) { tconv_tile_w(p->in[26] + (size_t)l * D * 512, 512, r / 2, r % 2, (bf16_t*)(ws + WS_WKV) + (size_t)(l * 1024) * D, D, tile); continue; } r -= C_XQ;
;         if (r < C_XQ) { tconv_tile_w(p->in[27] + (size_t)l * D * 512, 512, r / 2, r % 2, (bf16_t*)(ws + WS_WKV) + (size_t)(l * 1024 + 512) * D, D, tile); continue; } r -= C_XQ;
;         if (r < C_XO) { tconv_tile_w(p->in[28] + (size_t)l * 512 * D, D, r / 8, r % 8, (bf16_t*)(ws + WS_WXO) + (size_t)l * D * 512, 512, tile); continue; } r -= C_XO;
;         if (r < C_UP) { tconv_tile_w(p->in[30] + (size_t)l * D * DFF, DFF, r / 32, r % 32, (bf16_t*)(ws + WS_WUP) + (size_t)l * DFF * D, D, tile, p->in[29] + (size_t)l * D); continue; } r -= C_UP;
;         if (r < C_DN) { if (l == 0) tconv_tile_w(p->in[31] + (size_t)l * DFF * D, D, r / 8, r % 8, (bf16_t*)(ws + WS_WDN) + (size_t)l * D * DFF, DFF, tile); continue; } r -= C_DN;
;         bf16_t* wsm = (bf16_t*)(ws + WS_WSM) + (size_t)l * 1536 * 512;
;         if (r < C_GLU) { tconv_tile_w(p->in[14] + (size_t)l * 512 * 512, 512, r / 2, r % 2, wsm, 512, tile); continue; } r -= C_GLU;
.LBB0_17:
	s_mov_b64 s[14:15], s[0:1]
	s_load_dwordx2 s[12:13], s[14:15], 0x110
	v_writelane_b32 v254, s26, 2
	s_cmpk_gt_i32 s26, 0x2fbf
	s_cbranch_scc1 .LBB0_71
	s_mov_b32 s27, 0
	s_mov_b32 s28, 0
	s_mov_b32 s29, s26
	s_mov_b32 s63, s66
	s_mov_b32 s64, 0
	s_mov_b32 s65, 4
	v_writelane_b32 v255, 0, 62
.Ltc_entry:
	s_waitcnt lgkmcnt(0)
	v_and_b32_e32 v96, 63, v222
	v_lshlrev_b32_e32 v96, 4, v96
	v_lshrrev_b32_e32 v113, 6, v222
	v_and_b32_e32 v107, 7, v222
	v_readfirstlane_b32 s53, v113
	v_lshrrev_b32_e32 v108, 3, v222
	v_mul_u32_u24_e32 v106, 0x1010, v107
	v_lshl_add_u32 v106, v108, 2, v106
	v_lshlrev_b32_e32 v107, 4, v107
	s_lshl_b32 s54, s53, 3
	s_mul_i32 s2, s53, 0x1010
	v_add_u32_e32 v114, s2, v96
	v_add_u32_e32 v115, 0x404, v114
	v_add_u32_e32 v116, 0x808, v114
	v_add_u32_e32 v117, 0xc0c, v114
	v_add_u32_e32 v118, 0x8100, v114
	v_add_u32_e32 v119, 0x8100, v115
	v_add_u32_e32 v120, 0x8100, v116
	v_add_u32_e32 v121, 0x8100, v117
	s_mov_b32 s60, 1
	s_mov_b32 s42, 0
	s_mov_b32 s62, 1
	s_branch .Ltc_loadcnt_9
.Ltc_adv_2:
	s_cmp_lt_u32 s29, s30
	s_cbranch_scc1 .Ltc_found_3
	s_sub_u32 s29, s29, s30
	s_add_u32 s28, s28, 1
	s_mov_b32 s62, 1
	s_cmp_eq_u32 s28, 9
	s_cbranch_scc0 .Ltc_nodn_6
	s_cmp_eq_u32 s27, s64
	s_cbranch_scc1 .Ltc_nodn_6
	s_mov_b32 s28, 10
.Ltc_nodn_6:
	s_cmp_eq_u32 s28, 10
	s_cbranch_scc0 .Ltc_nowrap_7
	s_mov_b32 s28, 0
	s_add_u32 s27, s27, 1
	s_cmp_eq_u32 s27, s65
	s_cbranch_scc1 .Ltc_none_4
.Ltc_nowrap_7:
.Ltc_loadcnt_9:
	s_cmp_eq_u32 s28, 0
	s_cbranch_scc0 .Ltc_c_11
	s_mov_b32 s30, 448
	s_branch .Ltc_cdone_10

; __device__ __forceinline__ void phase0(PP p, unsigned char* shm) {
;     ...
;     constexpr int C_IN = 32 * 14, C_OUT = 32 * 8, C_XQ = 32 * 2, C_XO = 8 * 8, C_UP = 32 * 32, C_DN = 128 * 8, C_GLU = 8 * 2, C_POOL = 16, C_PW = 8 * 2;
;     constexpr int C_LAYER = C_IN + C_OUT + 3 * C_XQ + C_XO + C_UP + C_DN + C_GLU + C_POOL + C_PW;
;     for (int it = bid_fresh(); it < DEPTH * C_LAYER; it += gridDim.x) {
;         const int l = it / C_LAYER; int r = it % C_LAYER;
;         if (r < C_IN) { tconv_tile_w(p->in[5] + (size_t)l * D * INW, INW, r / 14, r % 14, (bf16_t*)(ws + WS_WIN) + (size_t)l * INW * D, D, tile, p->in[4] + (size_t)l * D); continue; } r -= C_IN;
;         if (r < C_OUT) { tconv_tile_w(p->in[23] + (size_t)l * D * D, D, r / 8, r % 8, (bf16_t*)(ws + WS_WOUT) + (size_t)l * D * D, D, tile, p->in[22] + (size_t)l * D); continue; } r -= C_OUT;
;         if (r < C_XQ) { tconv_tile_w(p->in[25] + (size_t)l * D * 512, 512, r / 2, r % 2, (bf16_t*)(ws + WS_WXQ) + (size_t)l * 512 * D, D, tile, p->in[24] + (size_t)l * D); continue; } r -= C_XQ;
;         if (r < C_XQ) { tconv_tile_w(p->in[26] + (size_t)l * D * 512, 512, r / 2, r % 2, (bf16_t*)(ws + WS_WKV) + (size_t)(l * 1024) * D, D, tile); continue; } r -= C_XQ;
;         if (r < C_XQ) { tconv_tile_w(p->in[27] + (size_t)l * D * 512, 512, r / 2, r % 2, (bf16_t*)(ws + WS_WKV) + (size_t)(l * 1024 + 512) * D, D, tile); continue; } r -= C_XQ;
;         if (r < C_XO) { tconv_tile_w(p->in[28] + (size_t)l * 512 * D, D, r / 8, r % 8, (bf16_t*)(ws + WS_WXO) + (size_t)l * D * 512, 512, tile); continue; } r -= C_XO;
;         if (r < C_UP) { tconv_tile_w(p->in[30] + (size_t)l * D * DFF, DFF, r / 32, r % 32, (bf16_t*)(ws + WS_WUP) + (size_t)l * DFF * D, D, tile, p->in[29] + (size_t)l * D); continue; } r -= C_UP;
;         if (r < C_DN) { if (l == 0) tconv_tile_w(p->in[31] + (size_t)l * DFF * D, D, r / 8, r % 8, (bf16_t*)(ws + WS_WDN) + (size_t)l * D * DFF, DFF, tile); continue; } r -= C_DN;
;         bf16_t* wsm = (bf16_t*)(ws + WS_WSM) + (size_t)l * 1536 * 512;
;         if (r < C_GLU) { tconv_tile_w(p->in[14] + (size_t)l * 512 * 512, 512, r / 2, r % 2, wsm, 512, tile); continue; } r -= C_GLU;
;         if (r < C_POOL) { const int gi = r >> 2, q = r & 3; tconv_tile(p->in[15] + (size_t)(l * 4 + gi) * 128 * 128, 128, q >> 1, q & 1, wsm + (size_t)(512 + gi * 128) * 512 + gi * 128, 512, tile); continue; } r -= C_POOL;
.Ltc_c_17:
	s_cmp_eq_u32 s28, 7
	s_cbranch_scc0 .Ltc_c_18
	s_mov_b32 s30, 16
	s_branch .Ltc_cdone_10

; __device__ __forceinline__ void phase0(PP p, unsigned char* shm) {
;     ...
;     constexpr int C_IN = 32 * 14, C_OUT = 32 * 8, C_XQ = 32 * 2, C_XO = 8 * 8, C_UP = 32 * 32, C_DN = 128 * 8, C_GLU = 8 * 2, C_POOL = 16, C_PW = 8 * 2;
;     constexpr int C_LAYER = C_IN + C_OUT + 3 * C_XQ + C_XO + C_UP + C_DN + C_GLU + C_POOL + C_PW;
;     for (int it = bid_fresh(); it < DEPTH * C_LAYER; it += gridDim.x) {
;         const int l = it / C_LAYER; int r = it % C_LAYER;
;         if (r < C_IN) { tconv_tile_w(p->in[5] + (size_t)l * D * INW, INW, r / 14, r % 14, (bf16_t*)(ws + WS_WIN) + (size_t)l * INW * D, D, tile, p->in[4] + (size_t)l * D); continue; } r -= C_IN;
;         if (r < C_OUT) { tconv_tile_w(p->in[23] + (size_t)l * D * D, D, r / 8, r % 8, (bf16_t*)(ws + WS_WOUT) + (size_t)l * D * D, D, tile, p->in[22] + (size_t)l * D); continue; } r -= C_OUT;
;         if (r < C_XQ) { tconv_tile_w(p->in[25] + (size_t)l * D * 512, 512, r / 2, r % 2, (bf16_t*)(ws + WS_WXQ) + (size_t)l * 512 * D, D, tile, p->in[24] + (size_t)l * D); continue; } r -= C_XQ;
;         if (r < C_XQ) { tconv_tile_w(p->in[26] + (size_t)l * D * 512, 512, r / 2, r % 2, (bf16_t*)(ws + WS_WKV) + (size_t)(l * 1024) * D, D, tile); continue; } r -= C_XQ;
;         if (r < C_XQ) { tconv_tile_w(p->in[27] + (size_t)l * D * 512, 512, r / 2, r % 2, (bf16_t*)(ws + WS_WKV) + (size_t)(l * 1024 + 512) * D, D, tile); continue; } r -= C_XQ;
;         if (r < C_XO) { tconv_tile_w(p->in[28] + (size_t)l * 512 * D, D, r / 8, r % 8, (bf16_t*)(ws + WS_WXO) + (size_t)l * D * 512, 512, tile); continue; } r -= C_XO;
;         if (r < C_UP) { tconv_tile_w(p->in[30] + (size_t)l * D * DFF, DFF, r / 32, r % 32, (bf16_t*)(ws + WS_WUP) + (size_t)l * DFF * D, D, tile, p->in[29] + (size_t)l * D); continue; } r -= C_UP;
;         if (r < C_DN) { if (l == 0) tconv_tile_w(p->in[31] + (size_t)l * DFF * D, D, r / 8, r % 8, (bf16_t*)(ws + WS_WDN) + (size_t)l * D * DFF, DFF, tile); continue; } r -= C_DN;
;         bf16_t* wsm = (bf16_t*)(ws + WS_WSM) + (size_t)l * 1536 * 512;
;         if (r < C_GLU) { tconv_tile_w(p->in[14] + (size_t)l * 512 * 512, 512, r / 2, r % 2, wsm, 512, tile); continue; } r -= C_GLU;
;         if (r < C_POOL) { const int gi = r >> 2, q = r & 3; tconv_tile(p->in[15] + (size_t)(l * 4 + gi) * 128 * 128, 128, q >> 1, q & 1, wsm + (size_t)(512 + gi * 128) * 512 + gi * 128, 512, tile); continue; } r -= C_POOL;
.Ltc_c_19:
	s_mov_b32 s30, 1024

; __device__ __forceinline__ void phase0(PP p, unsigned char* shm) {
;     ...
;         if (r < C_DN) { if (l == 0) tconv_tile_w(p->in[31] + (size_t)l * DFF * D, D, r / 8, r % 8, (bf16_t*)(ws + WS_WDN) + (size_t)l * D * DFF, DFF, tile); continue; } r -= C_DN;
;         bf16_t* wsm = (bf16_t*)(ws + WS_WSM) + (size_t)l * 1536 * 512;
;         if (r < C_GLU) { tconv_tile_w(p->in[14] + (size_t)l * 512 * 512, 512, r / 2, r % 2, wsm, 512, tile); continue; } r -= C_GLU;
;         if (r < C_POOL) { const int gi = r >> 2, q = r & 3; tconv_tile(p->in[15] + (size_t)(l * 4 + gi) * 128 * 128, 128, q >> 1, q & 1, wsm + (size_t)(512 + gi * 128) * 512 + gi * 128, 512, tile); continue; } r -= C_POOL;
;         tconv_tile_w(p->in[21] + (size_t)l * 512 * 512, 512, r / 2, r % 2, wsm + (size_t)1024 * 512, 512, tile);
.Ltc_k_28:
	s_cmp_eq_u32 s28, 7
	s_cbranch_scc0 .Ltc_k_29
	s_mov_b32 s30, 16
	s_mov_b32 s55, 0x70
	s_mov_b32 s34, 0x800
	s_mov_b32 s31, 0x8000
	s_mov_b32 s33, 2
	s_mov_b32 s35, 0x400
	s_mov_b32 s56, 0x17800000
	s_mov_b32 s57, 0x180000
	s_mov_b32 s58, 0x100000
	s_mov_b32 s42, 0x0
	s_branch .Ltc_segdone_21
.Ltc_k_29:
	s_cmp_eq_u32 s28, 8
	s_cbranch_scc0 .Ltc_k_30
	s_mov_b32 s30, 16
	s_mov_b32 s55, 0xa8
	s_mov_b32 s34, 0x800
	s_mov_b32 s31, 0x8000
	s_mov_b32 s33, 2
	s_mov_b32 s35, 0x400
	s_mov_b32 s56, 0x17900000
	s_mov_b32 s57, 0x180000
	s_mov_b32 s58, 0x100000
	s_mov_b32 s42, 0x0
	s_branch .Ltc_segdone_21
.Ltc_k_30:
	s_mov_b32 s30, 1024
	s_mov_b32 s55, 0xf8
	s_mov_b32 s34, 0x2000
	s_mov_b32 s31, 0x2000
	s_mov_b32 s33, 8
	s_mov_b32 s35, 0x4000
	s_mov_b32 s56, 0xf800000
	s_mov_b32 s57, 0x2000000
	s_mov_b32 s58, 0x4000000
	s_mov_b32 s42, 0x0

; __device__ __forceinline__ int tid_fresh() { int t = threadIdx.x; asm volatile("" : "+v"(t)); return t; }
; __device__ __forceinline__ int bid_fresh() { int t = blockIdx.x; asm volatile("" : "+s"(t)); return t; }
; __device__ __forceinline__ void tconv_tile_w(const float* src, int N, int kb, int nb, bf16_t* dst, int ldd, float* tile, const float* kscale = nullptr) {
;     const int tid = tid_fresh();
;     f32x4 v[8];
; #pragma unroll
;     for (int p = 0; p < 8; ++p) { const int idx = tid + 512 * p, r = idx >> 6, c4 = idx & 63;
;         v[p] = __builtin_nontemporal_load((const f32x4*)(src + (size_t)(kb * 64 + r) * N + nb * 256 + c4 * 4)); }
; __device__ __forceinline__ void phase0(PP p, unsigned char* shm) {
;     ...
;     for (int it = bid_fresh(); it < DEPTH * C_LAYER; it += gridDim.x) {
.Ltc_advend_5:
	s_cmp_eq_u32 s43, 0
	s_cbranch_scc1 .Ltc_exit_1
	v_mad_u32_u24 v97, s49, 0, v96
	v_mad_u32_u24 v98, s49, 1, v96
	v_mad_u32_u24 v99, s49, 2, v96
	v_mad_u32_u24 v100, s49, 3, v96
	v_mad_u32_u24 v101, s49, 4, v96
	v_mad_u32_u24 v102, s49, 5, v96
	v_mad_u32_u24 v103, s49, 6, v96
	v_mad_u32_u24 v104, s49, 7, v96
	global_load_dwordx4 v[0:3], v97, s[44:45] nt
	global_load_dwordx4 v[4:7], v98, s[44:45] nt
	global_load_dwordx4 v[8:11], v99, s[44:45] nt
	global_load_dwordx4 v[12:15], v100, s[44:45] nt
	global_load_dwordx4 v[16:19], v101, s[44:45] nt
	global_load_dwordx4 v[20:23], v102, s[44:45] nt
	global_load_dwordx4 v[24:27], v103, s[44:45] nt
	global_load_dwordx4 v[28:31], v104, s[44:45] nt
	s_waitcnt lgkmcnt(0)
	s_mov_b64 s[50:51], s[46:47]
	s_mov_b32 s52, s48
	s_mov_b32 s59, s61
	s_mov_b64 s[68:69], s[76:77]
	s_mov_b64 s[70:71], s[78:79]
	s_mov_b64 s[72:73], s[80:81]
	s_mov_b64 s[74:75], s[82:83]
.Ltc_loop_34:
	s_add_u32 s29, s29, s63
	s_mov_b32 s62, 0

; __device__ __forceinline__ unsigned pk2(float lo, float hi) { const hf32x2 v = {lo, hi}; return __builtin_bit_cast(unsigned, __builtin_convertvector(v, hbf16x2)); }
; __device__ __forceinline__ void tconv_tile_w(const float* src, int N, int kb, int nb, bf16_t* dst, int ldd, float* tile, const float* kscale = nullptr) {
;     ...
;     for (int p = 0; p < 8; ++p) { const int idx = tid + 512 * p, r = idx >> 6, c4 = idx & 63;
;         float* t = tile + r * 257 + c4 * 4; t[0] = v[p][0]; t[1] = v[p][1]; t[2] = v[p][2]; t[3] = v[p][3]; }
;     __syncthreads();
; #pragma unroll
;     for (int q = 0; q < 4; ++q) { const int id = tid + 512 * q, n = id >> 3, k8 = id & 7;
;         const float* s = tile + (k8 * 8) * 257 + n;
;         u32x4 o; o.x = pk2(s[0], s[257]); o.y = pk2(s[2 * 257], s[3 * 257]); o.z = pk2(s[4 * 257], s[5 * 257]); o.w = pk2(s[6 * 257], s[7 * 257]);
;         *(u32x4*)(dst + (size_t)(nb * 256 + n) * ldd + kb * 64 + k8 * 8) = o; }
;     __syncthreads();
.Ltc_pnosc_71:
	v_cvt_pk_bf16_f32 v64, v0, v4
	v_cvt_pk_bf16_f32 v65, v1, v5
	v_cvt_pk_bf16_f32 v66, v2, v6
	v_cvt_pk_bf16_f32 v67, v3, v7
	v_cvt_pk_bf16_f32 v68, v8, v12
	v_cvt_pk_bf16_f32 v69, v9, v13
	v_cvt_pk_bf16_f32 v70, v10, v14
	v_cvt_pk_bf16_f32 v71, v11, v15
	v_cvt_pk_bf16_f32 v72, v16, v20
	v_cvt_pk_bf16_f32 v73, v17, v21
	v_cvt_pk_bf16_f32 v74, v18, v22
	v_cvt_pk_bf16_f32 v75, v19, v23
	v_cvt_pk_bf16_f32 v76, v24, v28
	v_cvt_pk_bf16_f32 v77, v25, v29
	v_cvt_pk_bf16_f32 v78, v26, v30
	v_cvt_pk_bf16_f32 v79, v27, v31
	ds_write2_b32 v114, v64, v65 offset1:1
	ds_write2_b32 v114, v66, v67 offset0:2 offset1:3
	ds_write2_b32 v115, v68, v69 offset1:1
	ds_write2_b32 v115, v70, v71 offset0:2 offset1:3
	ds_write2_b32 v116, v72, v73 offset1:1
	ds_write2_b32 v116, v74, v75 offset0:2 offset1:3
	ds_write2_b32 v117, v76, v77 offset1:1
	ds_write2_b32 v117, v78, v79 offset0:2 offset1:3
	v_add_u32_e32 v113, 0, v108
	v_mad_u32_u24 v109, v113, s52, v107
	v_add_u32_e32 v113, 64, v108
	v_mad_u32_u24 v110, v113, s52, v107
	v_add_u32_e32 v113, 128, v108
	v_mad_u32_u24 v111, v113, s52, v107
	v_add_u32_e32 v113, 192, v108
	v_mad_u32_u24 v112, v113, s52, v107
	s_waitcnt lgkmcnt(0)
	s_barrier
	ds_read_b32 v80, v106 offset:0
	ds_read_b32 v81, v106 offset:1028
	ds_read_b32 v82, v106 offset:2056
	ds_read_b32 v83, v106 offset:3084
	ds_read_b32 v84, v106 offset:256
	ds_read_b32 v85, v106 offset:1284
	ds_read_b32 v86, v106 offset:2312
	ds_read_b32 v87, v106 offset:3340
	ds_read_b32 v88, v106 offset:512
	ds_read_b32 v89, v106 offset:1540
	ds_read_b32 v90, v106 offset:2568
	ds_read_b32 v91, v106 offset:3596
	ds_read_b32 v92, v106 offset:768
	ds_read_b32 v93, v106 offset:1796
	ds_read_b32 v94, v106 offset:2824
	ds_read_b32 v95, v106 offset:3852
	s_waitcnt lgkmcnt(12)
	global_store_dwordx4 v109, v[80:83], s[50:51]
	s_waitcnt lgkmcnt(8)
	global_store_dwordx4 v110, v[84:87], s[50:51]
	s_waitcnt lgkmcnt(4)
	global_store_dwordx4 v111, v[88:91], s[50:51]
	s_waitcnt lgkmcnt(0)
	global_store_dwordx4 v112, v[92:95], s[50:51]
	s_cmp_eq_u32 s43, 0
	s_cbranch_scc1 .Ltc_exit_1
	s_waitcnt lgkmcnt(0)
	s_mov_b64 s[50:51], s[46:47]
	s_mov_b32 s52, s48
	s_mov_b32 s59, s61
	s_mov_b64 s[68:69], s[76:77]
	s_mov_b64 s[70:71], s[78:79]
	s_mov_b64 s[72:73], s[80:81]
	s_mov_b64 s[74:75], s[82:83]
	s_add_u32 s29, s29, s63
	s_mov_b32 s62, 0

; __device__ __forceinline__ void phase0(PP p, unsigned char* shm) {
;     ...
;         if (r < C_POOL) { const int gi = r >> 2, q = r & 3; tconv_tile(p->in[15] + (size_t)(l * 4 + gi) * 128 * 128, 128, q >> 1, q & 1, wsm + (size_t)(512 + gi * 128) * 512 + gi * 128, 512, tile); continue; } r -= C_POOL;
.Ltc_exit_1:
	s_waitcnt vmcnt(0) lgkmcnt(0)
	s_barrier
	v_readlane_b32 s2, v255, 62
	s_nop 3
	s_cmp_eq_u32 s2, 0
	s_cbranch_scc1 .Ltc_ret0
	s_branch .Ltc_ret1
.Ltc_ret0:
	s_cmp_lt_u32 s26, 64
	s_cbranch_scc0 .Ltc_poolend_109
	s_load_dwordx2 s[2:3], s[14:15], 0x78
	s_lshr_b32 s4, s26, 4
	s_bfe_u32 s5, s26, 0x20002
	s_bfe_u32 s6, s26, 0x10001
	s_and_b32 s7, s26, 1
	s_lshl_b32 s18, s4, 2
	s_add_u32 s18, s18, s5
	s_lshl_b32 s18, s18, 16
	s_lshl_b32 s19, s6, 15
	s_add_u32 s18, s18, s19
	s_lshl_b32 s19, s7, 8
	s_add_u32 s18, s18, s19
	v_lshlrev_b32_e32 v0, 8, v107
	v_lshl_add_u32 v0, v108, 2, v0
	s_waitcnt lgkmcnt(0)
	s_add_u32 s2, s2, s18
	s_addc_u32 s3, s3, 0
	global_load_dword v1, v0, s[2:3] offset:0
	global_load_dword v2, v0, s[2:3] offset:512
	global_load_dword v3, v0, s[2:3] offset:1024
	global_load_dword v4, v0, s[2:3] offset:1536
	global_load_dword v5, v0, s[2:3] offset:2048
	global_load_dword v6, v0, s[2:3] offset:2560
	global_load_dword v7, v0, s[2:3] offset:3072
	global_load_dword v8, v0, s[2:3] offset:3584
	s_mul_i32 s18, s4, 0x180000
	s_add_u32 s18, s18, 0x17800000
	s_lshl_b32 s19, s5, 7
	s_lshl_b32 s20, s7, 6
	s_add_u32 s20, s20, s19
	s_add_u32 s20, s20, 0x200
	s_lshl_b32 s20, s20, 10
	s_add_u32 s18, s18, s20
	s_lshl_b32 s19, s5, 8
	s_add_u32 s18, s18, s19
	s_lshl_b32 s19, s6, 7
	s_add_u32 s18, s18, s19
	s_add_u32 s2, s12, s18
	s_addc_u32 s3, s13, 0
	v_lshl_add_u32 v9, v108, 10, v107
	s_waitcnt vmcnt(0)
	v_cvt_pk_bf16_f32 v10, v1, v2
	v_cvt_pk_bf16_f32 v11, v3, v4
	v_cvt_pk_bf16_f32 v12, v5, v6
	v_cvt_pk_bf16_f32 v13, v7, v8
	global_store_dwordx4 v9, v[10:13], s[2:3]

; __device__ __forceinline__ int bid_fresh() { int t = blockIdx.x; asm volatile("" : "+s"(t)); return t; }
; __global__ void __launch_bounds__(512, 2) hymba_fwd(Params p_unused) {
;     ...
;           { const int G = (int)gridDim.x, c = (int)bid_fresh(), nfull = 448 % G, nidle = (nfull == 0) ? 0 : G - nfull;
;             if (nidle > 0 && c >= nfull) { for (int r = c - nfull; r < 1024; r += nidle)
;                 tconv_tile_w(p->in[31] + (size_t)l * DFF * D, D, r / 8, r % 8, (bf16_t*)(ws + WS_WDN) + (size_t)l * D * DFF, DFF, (float*)shm); }
;             else if (nidle == 0) { for (int r = c; r < 1024; r += G) tconv_tile_w(p->in[31] + (size_t)l * DFF * D, D, r / 8, r % 8, (bf16_t*)(ws + WS_WDN) + (size_t)l * D * DFF, DFF, (float*)shm); } } }
.LBB0_286:
	s_mov_b32 s12, s30
	v_readlane_b32 s2, v254, 52
	s_cmp_lt_i32 s12, s2
	v_readlane_b32 s16, v254, 49
	s_cselect_b64 s[2:3], -1, 0
	v_readlane_b32 s17, v254, 50
	s_or_b64 s[16:17], s[2:3], s[16:17]
	s_mov_b64 s[2:3], -1
	s_and_b64 vcc, exec, s[16:17]
	s_cbranch_vccnz .LBB0_291
	v_readlane_b32 s2, v254, 52
	s_sub_i32 s2, s12, s2
	s_cmpk_gt_i32 s2, 0x3ff
	v_readlane_b32 s24, v255, 17
	v_readlane_b32 s25, v254, 54
	s_movk_i32 s34, 0x404
	s_cbranch_scc1 .LBB0_290
	v_writelane_b32 v124, s2, 0
	v_writelane_b32 v124, s3, 1
	v_writelane_b32 v124, s4, 2
	v_writelane_b32 v124, s5, 3
	v_writelane_b32 v124, s6, 4
	v_writelane_b32 v124, s7, 5
	v_writelane_b32 v124, s12, 6
	v_writelane_b32 v124, s13, 7
	v_writelane_b32 v124, s14, 8
	v_writelane_b32 v124, s15, 9
	v_writelane_b32 v124, s27, 10
	v_writelane_b32 v124, s28, 11
	v_writelane_b32 v124, s29, 12
	v_writelane_b32 v124, s30, 13
	v_writelane_b32 v124, s31, 14
	v_writelane_b32 v124, s33, 15
	v_writelane_b32 v124, s34, 16
	v_writelane_b32 v124, s35, 17
	v_writelane_b32 v124, s36, 18
	v_writelane_b32 v124, s37, 19
	v_writelane_b32 v124, s38, 20
	v_writelane_b32 v124, s39, 21
	v_writelane_b32 v124, s40, 22
	v_writelane_b32 v124, s41, 23
	v_writelane_b32 v124, s42, 24
	v_writelane_b32 v124, s43, 25
	v_writelane_b32 v124, s44, 26
	v_writelane_b32 v124, s45, 27
	v_writelane_b32 v124, s46, 28
	v_writelane_b32 v124, s47, 29
	v_writelane_b32 v124, s48, 30
	v_writelane_b32 v124, s49, 31
	v_writelane_b32 v124, s50, 32
	v_writelane_b32 v124, s51, 33
	v_writelane_b32 v124, s52, 34
	v_writelane_b32 v124, s53, 35
	v_writelane_b32 v124, s54, 36
	v_writelane_b32 v124, s55, 37
	v_writelane_b32 v124, s56, 38
	v_writelane_b32 v124, s57, 39
	v_writelane_b32 v124, s58, 40
	v_writelane_b32 v124, s59, 41
	v_writelane_b32 v124, s60, 42
	v_writelane_b32 v124, s61, 43
	v_writelane_b32 v124, s62, 44
	v_writelane_b32 v124, s63, 45
	v_writelane_b32 v124, s64, 46
	v_writelane_b32 v124, s65, 47
	v_writelane_b32 v124, s68, 48
	v_writelane_b32 v124, s69, 49
	v_writelane_b32 v124, s70, 50
	v_writelane_b32 v124, s71, 51
	v_writelane_b32 v124, s72, 52
	v_writelane_b32 v124, s73, 53
	v_writelane_b32 v124, s74, 54
	v_writelane_b32 v124, s75, 55
	v_writelane_b32 v124, s76, 56
	v_writelane_b32 v124, s77, 57
	v_writelane_b32 v124, s78, 58
	v_writelane_b32 v124, s79, 59
	v_writelane_b32 v124, s80, 60
	v_writelane_b32 v124, s81, 61
	v_writelane_b32 v124, s82, 62
	v_writelane_b32 v124, s83, 63
	v_readlane_b32 s29, v254, 2
	v_readlane_b32 s3, v254, 52
	v_readlane_b32 s27, v255, 20
	v_readlane_b32 s63, v255, 17
	s_mov_b64 s[14:15], s[0:1]
	s_load_dwordx2 s[12:13], s[0:1], 0x110
	s_nop 3
	s_sub_u32 s29, s29, s3
	s_mov_b32 s28, 9
	s_mov_b32 s64, s27
	s_add_u32 s65, s27, 1
	s_min_u32 s65, s65, 4
	v_writelane_b32 v255, 1, 62
	s_branch .Ltc_entry
.Ltc_ret1:
	v_readlane_b32 s2, v124, 0
	v_readlane_b32 s3, v124, 1
	v_readlane_b32 s4, v124, 2
	v_readlane_b32 s5, v124, 3
	v_readlane_b32 s6, v124, 4
	v_readlane_b32 s7, v124, 5
	v_readlane_b32 s12, v124, 6
	v_readlane_b32 s13, v124, 7
	v_readlane_b32 s14, v124, 8
	v_readlane_b32 s15, v124, 9
	v_readlane_b32 s27, v124, 10
	v_readlane_b32 s28, v124, 11
	v_readlane_b32 s29, v124, 12
	v_readlane_b32 s30, v124, 13
	v_readlane_b32 s31, v124, 14
	v_readlane_b32 s33, v124, 15
	v_readlane_b32 s34, v124, 16
	v_readlane_b32 s35, v124, 17
	v_readlane_b32 s36, v124, 18
	v_readlane_b32 s37, v124, 19
	v_readlane_b32 s38, v124, 20
	v_readlane_b32 s39, v124, 21
	v_readlane_b32 s40, v124, 22
	v_readlane_b32 s41, v124, 23
	v_readlane_b32 s42, v124, 24
	v_readlane_b32 s43, v124, 25
	v_readlane_b32 s44, v124, 26
	v_readlane_b32 s45, v124, 27
	v_readlane_b32 s46, v124, 28
	v_readlane_b32 s47, v124, 29
	v_readlane_b32 s48, v124, 30
	v_readlane_b32 s49, v124, 31
	v_readlane_b32 s50, v124, 32
	v_readlane_b32 s51, v124, 33
	v_readlane_b32 s52, v124, 34
	v_readlane_b32 s53, v124, 35
	v_readlane_b32 s54, v124, 36
	v_readlane_b32 s55, v124, 37
	v_readlane_b32 s56, v124, 38
	v_readlane_b32 s57, v124, 39
	v_readlane_b32 s58, v124, 40
	v_readlane_b32 s59, v124, 41
	v_readlane_b32 s60, v124, 42
	v_readlane_b32 s61, v124, 43
	v_readlane_b32 s62, v124, 44
	v_readlane_b32 s63, v124, 45
	v_readlane_b32 s64, v124, 46
	v_readlane_b32 s65, v124, 47
	v_readlane_b32 s68, v124, 48
	v_readlane_b32 s69, v124, 49
	v_readlane_b32 s70, v124, 50
	v_readlane_b32 s71, v124, 51
	v_readlane_b32 s72, v124, 52
	v_readlane_b32 s73, v124, 53
	v_readlane_b32 s74, v124, 54
	v_readlane_b32 s75, v124, 55
	v_readlane_b32 s76, v124, 56
	v_readlane_b32 s77, v124, 57
	v_readlane_b32 s78, v124, 58
	v_readlane_b32 s79, v124, 59
	v_readlane_b32 s80, v124, 60
	v_readlane_b32 s81, v124, 61
	v_readlane_b32 s82, v124, 62
	v_readlane_b32 s83, v124, 63
	v_mov_b32_e32 v1, 0
	s_nop 3
